# GLA chunk: the 16 cumulative-gate LDS reads per chunk issued together into spare VGPRs instead of 16 read-wait steps
# speedup vs baseline: 1.0023x; 1.0007x over previous
.LBB0_242:
	s_or_b64 exec, exec, s[68:69]
	s_waitcnt lgkmcnt(0)
	s_barrier
	v_add_u32_e32 v86, v122, v119
	ds_read_b128 v[78:81], v137 offset:36864
	ds_read_b128 v[74:77], v137 offset:36896
	ds_read_b128 v[70:73], v137 offset:36928
	ds_read_b128 v[66:69], v137 offset:36960
	ds_read_b128 v[34:37], v86 offset:27648
	ds_read_b128 v[82:85], v86 offset:27680
	v_add_u32_e32 v139, v122, v121
	s_waitcnt lgkmcnt(1)
	v_mfma_f32_32x32x16_bf16 v[34:49], v[34:37], v[78:81], 0
	s_add_i32 s74, s74, 1
	s_cmp_eq_u32 s74, 4
	s_waitcnt lgkmcnt(0)
	v_mfma_f32_32x32x16_bf16 v[34:49], v[82:85], v[74:77], v[34:49]
	ds_read_b128 v[82:85], v86 offset:27712
	s_waitcnt lgkmcnt(0)
	v_mfma_f32_32x32x16_bf16 v[34:49], v[82:85], v[70:73], v[34:49]
	ds_read_b128 v[82:85], v86 offset:27744
	ds_read2_b64 v[86:89], v139 offset1:2
	ds_read2_b64 v[90:93], v139 offset0:4 offset1:6
	ds_read2_b64 v[94:97], v139 offset0:8 offset1:10
	s_waitcnt lgkmcnt(3)
	v_mfma_f32_32x32x16_bf16 v[34:49], v[82:85], v[66:69], v[34:49]
	v_cvt_pk_bf16_f32 v82, v18, v19
	v_cvt_pk_bf16_f32 v83, v20, v21
	v_cvt_pk_bf16_f32 v84, v22, v23
	v_cvt_pk_bf16_f32 v85, v24, v25
	s_waitcnt lgkmcnt(2)
	s_nop 0
	v_mfma_f32_32x32x16_bf16 v[34:49], v[86:89], v[82:85], v[34:49]
	ds_read2_b64 v[86:89], v139 offset0:12 offset1:14
	v_add_u32_e32 v139, 0xd800, v124
	v_add_u32_e32 v176, 0xd800, v124
	ds_read2_b32 v[144:145], v176 offset0:0 offset1:1
	ds_read2_b32 v[146:147], v176 offset0:2 offset1:3
	ds_read2_b32 v[148:149], v176 offset0:8 offset1:9
	ds_read2_b32 v[150:151], v176 offset0:10 offset1:11
	ds_read2_b32 v[152:153], v176 offset0:16 offset1:17
	ds_read2_b32 v[154:155], v176 offset0:18 offset1:19
	ds_read2_b32 v[156:157], v176 offset0:24 offset1:25
	ds_read2_b32 v[158:159], v176 offset0:26 offset1:27
	ds_read2_b32 v[160:161], v176 offset0:32 offset1:33
	ds_read2_b32 v[162:163], v176 offset0:34 offset1:35
	ds_read2_b32 v[164:165], v176 offset0:40 offset1:41
	ds_read2_b32 v[166:167], v176 offset0:42 offset1:43
	ds_read2_b32 v[168:169], v176 offset0:48 offset1:49
	ds_read2_b32 v[170:171], v176 offset0:50 offset1:51
	ds_read2_b32 v[172:173], v176 offset0:56 offset1:57
	ds_read2_b32 v[174:175], v176 offset0:58 offset1:59
	v_cvt_pk_bf16_f32 v82, v26, v27
	v_cvt_pk_bf16_f32 v83, v28, v29
	v_cvt_pk_bf16_f32 v84, v30, v31
	v_cvt_pk_bf16_f32 v85, v32, v33
	s_waitcnt lgkmcnt(0)
	v_mov_b32_e32 v140, v144
	v_mov_b32_e32 v141, v145
	v_mul_f32_e32 v139, 0x3fb8aa3b, v140
	v_exp_f32_e32 v140, v139
	v_mul_f32_e32 v139, 0x3fb8aa3b, v141
	v_exp_f32_e32 v141, v139
	v_add_u32_e32 v139, 0xd808, v124
	v_mfma_f32_32x32x16_bf16 v[34:49], v[90:93], v[82:85], v[34:49]
	v_cvt_pk_bf16_f32 v90, v2, v3
	v_mul_f32_e64 v18, v18, v140
	v_mul_f32_e64 v19, v19, v141
	s_nop 0
	v_cvt_pk_bf16_f32 v91, v4, v5
	v_cvt_pk_bf16_f32 v92, v6, v7
	v_cvt_pk_bf16_f32 v93, v8, v9
	v_cvt_pk_bf16_f32 v82, v10, v11
	s_waitcnt lgkmcnt(0)
	v_mov_b32_e32 v140, v146
	v_mov_b32_e32 v141, v147
	v_mul_f32_e32 v139, 0x3fb8aa3b, v140
	v_exp_f32_e32 v140, v139
	v_mul_f32_e32 v139, 0x3fb8aa3b, v141
	v_exp_f32_e32 v141, v139
	v_add_u32_e32 v139, 0xd820, v124
	v_cvt_pk_bf16_f32 v83, v12, v13
	v_cvt_pk_bf16_f32 v84, v14, v15
	v_pk_mul_f32 v[20:21], v[20:21], v[140:141]
	s_nop 0
	v_cvt_pk_bf16_f32 v85, v16, v17
	v_mfma_f32_32x32x16_bf16 v[34:49], v[94:97], v[90:93], v[34:49]
	s_waitcnt lgkmcnt(0)
	v_mov_b32_e32 v140, v148
	v_mov_b32_e32 v141, v149
	v_mul_f32_e32 v139, 0x3fb8aa3b, v140
	v_exp_f32_e32 v140, v139
	v_mul_f32_e32 v139, 0x3fb8aa3b, v141
	v_exp_f32_e32 v141, v139
	v_add_u32_e32 v139, 0xd828, v124
	v_mfma_f32_32x32x16_bf16 v[34:49], v[86:89], v[82:85], v[34:49]
	v_mul_f32_e64 v22, v22, v140
	v_mul_f32_e64 v23, v23, v141
	s_nop 0
	s_waitcnt lgkmcnt(0)
	v_mov_b32_e32 v140, v150
	v_mov_b32_e32 v141, v151
	v_mul_f32_e32 v139, 0x3fb8aa3b, v140
	v_exp_f32_e32 v140, v139
	v_mul_f32_e32 v139, 0x3fb8aa3b, v141
	v_exp_f32_e32 v141, v139
	v_add_u32_e32 v139, 0xd840, v124
	s_nop 2
	v_cvt_pk_bf16_f32 v34, v34, s0
	v_pk_mul_f32 v[24:25], v[24:25], v[140:141]
	s_nop 0
	s_waitcnt lgkmcnt(0)
	v_mov_b32_e32 v140, v152
	v_mov_b32_e32 v141, v153
	v_mul_f32_e32 v139, 0x3fb8aa3b, v140
	v_exp_f32_e32 v140, v139
	v_mul_f32_e32 v139, 0x3fb8aa3b, v141
	v_exp_f32_e32 v141, v139
	v_add_u32_e32 v139, 0xd848, v124
	v_pk_mul_f32 v[26:27], v[26:27], v[140:141]
	s_nop 0
	s_waitcnt lgkmcnt(0)
	v_mov_b32_e32 v140, v154
	v_mov_b32_e32 v141, v155
	v_mul_f32_e32 v139, 0x3fb8aa3b, v140
	v_exp_f32_e32 v140, v139
	v_mul_f32_e32 v139, 0x3fb8aa3b, v141
	v_exp_f32_e32 v141, v139
	v_add_u32_e32 v139, 0xd860, v124
	v_pk_mul_f32 v[28:29], v[28:29], v[140:141]
	s_nop 0
	s_waitcnt lgkmcnt(0)
	v_mov_b32_e32 v140, v156
	v_mov_b32_e32 v141, v157
	v_mul_f32_e32 v139, 0x3fb8aa3b, v140
	v_exp_f32_e32 v140, v139
	v_mul_f32_e32 v139, 0x3fb8aa3b, v141
	v_exp_f32_e32 v141, v139
	v_add_u32_e32 v139, 0xd868, v124
	v_pk_mul_f32 v[30:31], v[30:31], v[140:141]
	s_nop 0
	s_waitcnt lgkmcnt(0)
	v_mov_b32_e32 v140, v158
	v_mov_b32_e32 v141, v159
	v_mul_f32_e32 v139, 0x3fb8aa3b, v140
	v_exp_f32_e32 v140, v139
	v_mul_f32_e32 v139, 0x3fb8aa3b, v141
	v_exp_f32_e32 v141, v139
	v_add_u32_e32 v139, 0xd880, v124
	v_pk_mul_f32 v[32:33], v[32:33], v[140:141]
	ds_read_b128 v[140:143], v138 offset:18432
	ds_read_b128 v[144:147], v138 offset:18464
	s_waitcnt lgkmcnt(1)
	v_mfma_f32_32x32x16_bf16 v[18:33], v[140:143], v[78:81], v[18:33]
	ds_read_b128 v[140:143], v138 offset:18496
	s_waitcnt lgkmcnt(1)
	v_mfma_f32_32x32x16_bf16 v[18:33], v[144:147], v[74:77], v[18:33]
	s_waitcnt lgkmcnt(0)
	v_mfma_f32_32x32x16_bf16 v[18:33], v[140:143], v[70:73], v[18:33]
	ds_read_b128 v[140:143], v138 offset:18528
	s_waitcnt lgkmcnt(0)
	v_mfma_f32_32x32x16_bf16 v[18:33], v[140:143], v[66:69], v[18:33]
	s_nop 0
	s_waitcnt lgkmcnt(0)
	v_mov_b32_e32 v140, v160
	v_mov_b32_e32 v141, v161
	v_mul_f32_e32 v139, 0x3fb8aa3b, v140
	v_exp_f32_e32 v140, v139
	v_mul_f32_e32 v139, 0x3fb8aa3b, v141
	v_exp_f32_e32 v141, v139
	v_add_u32_e32 v139, 0xd888, v124
	v_pk_mul_f32 v[2:3], v[2:3], v[140:141]
	s_nop 0
	s_waitcnt lgkmcnt(0)
	v_mov_b32_e32 v140, v162
	v_mov_b32_e32 v141, v163
	v_mul_f32_e32 v139, 0x3fb8aa3b, v140
	v_exp_f32_e32 v140, v139
	v_mul_f32_e32 v139, 0x3fb8aa3b, v141
	v_exp_f32_e32 v141, v139
	v_add_u32_e32 v139, 0xd8a0, v124
	v_pk_mul_f32 v[4:5], v[4:5], v[140:141]
	s_nop 0
	s_waitcnt lgkmcnt(0)
	v_mov_b32_e32 v140, v164
	v_mov_b32_e32 v141, v165
	v_mul_f32_e32 v139, 0x3fb8aa3b, v140
	v_exp_f32_e32 v140, v139
	v_mul_f32_e32 v139, 0x3fb8aa3b, v141
	v_exp_f32_e32 v141, v139
	v_add_u32_e32 v139, 0xd8a8, v124
	v_pk_mul_f32 v[6:7], v[6:7], v[140:141]
	s_nop 0
	s_waitcnt lgkmcnt(0)
	v_mov_b32_e32 v140, v166
	v_mov_b32_e32 v141, v167
	v_mul_f32_e32 v139, 0x3fb8aa3b, v140
	v_exp_f32_e32 v140, v139
	v_mul_f32_e32 v139, 0x3fb8aa3b, v141
	v_exp_f32_e32 v141, v139
	v_add_u32_e32 v139, 0xd8c0, v124
	v_pk_mul_f32 v[8:9], v[8:9], v[140:141]
	s_nop 0
	s_waitcnt lgkmcnt(0)
	v_mov_b32_e32 v140, v168
	v_mov_b32_e32 v141, v169
	v_mul_f32_e32 v139, 0x3fb8aa3b, v140
	v_exp_f32_e32 v140, v139
	v_mul_f32_e32 v139, 0x3fb8aa3b, v141
	v_exp_f32_e32 v141, v139
	v_add_u32_e32 v139, 0xd8c8, v124
	v_pk_mul_f32 v[10:11], v[10:11], v[140:141]
	s_nop 0
	s_waitcnt lgkmcnt(0)
	v_mov_b32_e32 v140, v170
	v_mov_b32_e32 v141, v171
	v_mul_f32_e32 v139, 0x3fb8aa3b, v140
	v_exp_f32_e32 v140, v139
	v_mul_f32_e32 v139, 0x3fb8aa3b, v141
	v_exp_f32_e32 v141, v139
	v_add_u32_e32 v139, 0xd8e0, v124
	v_pk_mul_f32 v[12:13], v[12:13], v[140:141]
	s_nop 0
	s_waitcnt lgkmcnt(0)
	v_mov_b32_e32 v140, v172
	v_mov_b32_e32 v141, v173
	v_mul_f32_e32 v139, 0x3fb8aa3b, v140
	v_exp_f32_e32 v140, v139
	v_mul_f32_e32 v139, 0x3fb8aa3b, v141
	v_exp_f32_e32 v141, v139
	v_add_u32_e32 v139, 0xd8e8, v124
	v_pk_mul_f32 v[14:15], v[14:15], v[140:141]
	s_nop 0
	s_waitcnt lgkmcnt(0)
	v_mov_b32_e32 v140, v174
	v_mov_b32_e32 v141, v175
	v_mul_f32_e32 v139, 0x3fb8aa3b, v140
	v_exp_f32_e32 v140, v139
	v_mul_f32_e32 v139, 0x3fb8aa3b, v141
	v_exp_f32_e32 v141, v139
	s_nop 0
	v_pk_mul_f32 v[16:17], v[16:17], v[140:141]
	ds_read_b128 v[140:143], v138 offset:23040
	s_waitcnt lgkmcnt(0)
	v_mfma_f32_32x32x16_bf16 v[2:17], v[140:143], v[78:81], v[2:17]
	ds_read_b128 v[78:81], v138 offset:23072
	s_waitcnt lgkmcnt(0)
	v_mfma_f32_32x32x16_bf16 v[2:17], v[78:81], v[74:77], v[2:17]
	ds_read_b128 v[74:77], v138 offset:23104
	s_waitcnt lgkmcnt(0)
	v_mfma_f32_32x32x16_bf16 v[2:17], v[74:77], v[70:73], v[2:17]
	ds_read_b128 v[70:73], v138 offset:23136
	s_waitcnt lgkmcnt(0)
	v_mfma_f32_32x32x16_bf16 v[2:17], v[70:73], v[66:69], v[2:17]
	v_lshl_add_u32 v66, s62, 6, v123
	v_ashrrev_i32_e32 v67, 31, v66
	v_lshlrev_b64 v[66:67], 10, v[66:67]
	v_lshl_add_u64 v[66:67], v[110:111], 0, v[66:67]
	global_store_short v[66:67], v34, off
	v_cvt_pk_bf16_f32 v34, v35, s0
	global_store_short v[66:67], v34, off offset:1024
	v_cvt_pk_bf16_f32 v34, v36, s0
	global_store_short v[66:67], v34, off offset:2048
	v_cvt_pk_bf16_f32 v34, v37, s0
	global_store_short v[66:67], v34, off offset:3072
	v_add_co_u32_e32 v34, vcc, s82, v66
	v_cvt_pk_bf16_f32 v36, v38, s0
	s_nop 0
	v_addc_co_u32_e32 v35, vcc, 0, v67, vcc
	global_store_short v[34:35], v36, off
	v_cvt_pk_bf16_f32 v36, v39, s0
	global_store_short v[34:35], v36, off offset:1024
	v_cvt_pk_bf16_f32 v36, v40, s0
	global_store_short v[34:35], v36, off offset:2048
	v_cvt_pk_bf16_f32 v36, v41, s0
	global_store_short v[34:35], v36, off offset:3072
	v_add_co_u32_e32 v34, vcc, s81, v66
	v_cvt_pk_bf16_f32 v36, v42, s0
	s_nop 0
	v_addc_co_u32_e32 v35, vcc, 0, v67, vcc
	global_store_short v[34:35], v36, off
	v_cvt_pk_bf16_f32 v36, v43, s0
	global_store_short v[34:35], v36, off offset:1024
	v_cvt_pk_bf16_f32 v36, v44, s0
	global_store_short v[34:35], v36, off offset:2048
	v_cvt_pk_bf16_f32 v36, v45, s0
	global_store_short v[34:35], v36, off offset:3072
	v_add_co_u32_e32 v34, vcc, s89, v66
	v_cvt_pk_bf16_f32 v36, v46, s0
	s_nop 0
	v_addc_co_u32_e32 v35, vcc, 0, v67, vcc
	global_store_short v[34:35], v36, off
	v_cvt_pk_bf16_f32 v36, v47, s0
	global_store_short v[34:35], v36, off offset:1024
	v_cvt_pk_bf16_f32 v36, v48, s0
	global_store_short v[34:35], v36, off offset:2048
	v_cvt_pk_bf16_f32 v36, v49, s0
	global_store_short v[34:35], v36, off offset:3072
	s_waitcnt vmcnt(20)
	v_mov_b64_e32 v[38:39], v[62:63]
	s_waitcnt vmcnt(19)
	v_mov_b64_e32 v[34:35], v[58:59]
	v_mov_b64_e32 v[40:41], v[64:65]
	v_mov_b64_e32 v[36:37], v[60:61]
	s_cbranch_scc1 .LBB0_257

.LBB0_319:
	s_or_b64 exec, exec, s[68:69]
	s_waitcnt lgkmcnt(0)
	s_barrier
	v_add_u32_e32 v86, v118, v115
	ds_read_b128 v[78:81], v133 offset:36864
	ds_read_b128 v[74:77], v133 offset:36896
	ds_read_b128 v[70:73], v133 offset:36928
	ds_read_b128 v[66:69], v133 offset:36960
	ds_read_b128 v[34:37], v86 offset:27648
	ds_read_b128 v[82:85], v86 offset:27680
	v_add_u32_e32 v135, v118, v117
	s_waitcnt lgkmcnt(1)
	v_mfma_f32_32x32x16_bf16 v[34:49], v[34:37], v[78:81], 0
	s_add_i32 s2, s2, 1
	s_cmp_lg_u32 s2, 64
	s_waitcnt lgkmcnt(0)
	v_mfma_f32_32x32x16_bf16 v[34:49], v[82:85], v[74:77], v[34:49]
	ds_read_b128 v[82:85], v86 offset:27712
	s_waitcnt lgkmcnt(0)
	v_mfma_f32_32x32x16_bf16 v[34:49], v[82:85], v[70:73], v[34:49]
	ds_read_b128 v[82:85], v86 offset:27744
	ds_read2_b64 v[86:89], v135 offset1:2
	ds_read2_b64 v[90:93], v135 offset0:4 offset1:6
	ds_read2_b64 v[94:97], v135 offset0:8 offset1:10
	s_waitcnt lgkmcnt(3)
	v_mfma_f32_32x32x16_bf16 v[34:49], v[82:85], v[66:69], v[34:49]
	v_cvt_pk_bf16_f32 v82, v2, v3
	v_cvt_pk_bf16_f32 v83, v4, v5
	v_cvt_pk_bf16_f32 v84, v6, v7
	v_cvt_pk_bf16_f32 v85, v8, v9
	s_waitcnt lgkmcnt(2)
	s_nop 0
	v_mfma_f32_32x32x16_bf16 v[34:49], v[86:89], v[82:85], v[34:49]
	ds_read2_b64 v[86:89], v135 offset0:12 offset1:14
	v_add_u32_e32 v135, 0xd800, v120
	v_add_u32_e32 v176, 0xd800, v120
	ds_read2_b32 v[144:145], v176 offset0:0 offset1:1
	ds_read2_b32 v[146:147], v176 offset0:2 offset1:3
	ds_read2_b32 v[148:149], v176 offset0:8 offset1:9
	ds_read2_b32 v[150:151], v176 offset0:10 offset1:11
	ds_read2_b32 v[152:153], v176 offset0:16 offset1:17
	ds_read2_b32 v[154:155], v176 offset0:18 offset1:19
	ds_read2_b32 v[156:157], v176 offset0:24 offset1:25
	ds_read2_b32 v[158:159], v176 offset0:26 offset1:27
	ds_read2_b32 v[160:161], v176 offset0:32 offset1:33
	ds_read2_b32 v[162:163], v176 offset0:34 offset1:35
	ds_read2_b32 v[164:165], v176 offset0:40 offset1:41
	ds_read2_b32 v[166:167], v176 offset0:42 offset1:43
	ds_read2_b32 v[168:169], v176 offset0:48 offset1:49
	ds_read2_b32 v[170:171], v176 offset0:50 offset1:51
	ds_read2_b32 v[172:173], v176 offset0:56 offset1:57
	ds_read2_b32 v[174:175], v176 offset0:58 offset1:59
	v_cvt_pk_bf16_f32 v82, v10, v11
	v_cvt_pk_bf16_f32 v83, v12, v13
	v_cvt_pk_bf16_f32 v84, v14, v15
	v_cvt_pk_bf16_f32 v85, v16, v17
	s_waitcnt lgkmcnt(0)
	v_mov_b32_e32 v136, v144
	v_mov_b32_e32 v137, v145
	v_mul_f32_e32 v135, 0x3fb8aa3b, v136
	v_exp_f32_e32 v136, v135
	v_mul_f32_e32 v135, 0x3fb8aa3b, v137
	v_exp_f32_e32 v137, v135
	v_add_u32_e32 v135, 0xd808, v120
	v_mfma_f32_32x32x16_bf16 v[34:49], v[90:93], v[82:85], v[34:49]
	v_cvt_pk_bf16_f32 v90, v18, v19
	v_mul_f32_e64 v2, v2, v136
	v_mul_f32_e64 v3, v3, v137
	s_nop 0
	v_cvt_pk_bf16_f32 v91, v20, v21
	v_cvt_pk_bf16_f32 v92, v22, v23
	v_cvt_pk_bf16_f32 v93, v24, v25
	v_cvt_pk_bf16_f32 v82, v26, v27
	s_waitcnt lgkmcnt(0)
	v_mov_b32_e32 v136, v146
	v_mov_b32_e32 v137, v147
	v_mul_f32_e32 v135, 0x3fb8aa3b, v136
	v_exp_f32_e32 v136, v135
	v_mul_f32_e32 v135, 0x3fb8aa3b, v137
	v_exp_f32_e32 v137, v135
	v_add_u32_e32 v135, 0xd820, v120
	v_cvt_pk_bf16_f32 v83, v28, v29
	v_cvt_pk_bf16_f32 v84, v30, v31
	v_pk_mul_f32 v[4:5], v[4:5], v[136:137]
	s_nop 0
	v_cvt_pk_bf16_f32 v85, v32, v33
	v_mfma_f32_32x32x16_bf16 v[34:49], v[94:97], v[90:93], v[34:49]
	s_waitcnt lgkmcnt(0)
	v_mov_b32_e32 v136, v148
	v_mov_b32_e32 v137, v149
	v_mul_f32_e32 v135, 0x3fb8aa3b, v136
	v_exp_f32_e32 v136, v135
	v_mul_f32_e32 v135, 0x3fb8aa3b, v137
	v_exp_f32_e32 v137, v135
	v_add_u32_e32 v135, 0xd828, v120
	v_mfma_f32_32x32x16_bf16 v[34:49], v[86:89], v[82:85], v[34:49]
	v_mul_f32_e64 v6, v6, v136
	v_mul_f32_e64 v7, v7, v137
	s_nop 0
	s_waitcnt lgkmcnt(0)
	v_mov_b32_e32 v136, v150
	v_mov_b32_e32 v137, v151
	v_mul_f32_e32 v135, 0x3fb8aa3b, v136
	v_exp_f32_e32 v136, v135
	v_mul_f32_e32 v135, 0x3fb8aa3b, v137
	v_exp_f32_e32 v137, v135
	v_add_u32_e32 v135, 0xd840, v120
	s_nop 2
	v_cvt_pk_bf16_f32 v34, v34, s0
	v_pk_mul_f32 v[8:9], v[8:9], v[136:137]
	s_nop 0
	s_waitcnt lgkmcnt(0)
	v_mov_b32_e32 v136, v152
	v_mov_b32_e32 v137, v153
	v_mul_f32_e32 v135, 0x3fb8aa3b, v136
	v_exp_f32_e32 v136, v135
	v_mul_f32_e32 v135, 0x3fb8aa3b, v137
	v_exp_f32_e32 v137, v135
	v_add_u32_e32 v135, 0xd848, v120
	v_pk_mul_f32 v[10:11], v[10:11], v[136:137]
	s_nop 0
	s_waitcnt lgkmcnt(0)
	v_mov_b32_e32 v136, v154
	v_mov_b32_e32 v137, v155
	v_mul_f32_e32 v135, 0x3fb8aa3b, v136
	v_exp_f32_e32 v136, v135
	v_mul_f32_e32 v135, 0x3fb8aa3b, v137
	v_exp_f32_e32 v137, v135
	v_add_u32_e32 v135, 0xd860, v120
	v_pk_mul_f32 v[12:13], v[12:13], v[136:137]
	s_nop 0
	s_waitcnt lgkmcnt(0)
	v_mov_b32_e32 v136, v156
	v_mov_b32_e32 v137, v157
	v_mul_f32_e32 v135, 0x3fb8aa3b, v136
	v_exp_f32_e32 v136, v135
	v_mul_f32_e32 v135, 0x3fb8aa3b, v137
	v_exp_f32_e32 v137, v135
	v_add_u32_e32 v135, 0xd868, v120
	v_pk_mul_f32 v[14:15], v[14:15], v[136:137]
	s_nop 0
	s_waitcnt lgkmcnt(0)
	v_mov_b32_e32 v136, v158
	v_mov_b32_e32 v137, v159
	v_mul_f32_e32 v135, 0x3fb8aa3b, v136
	v_exp_f32_e32 v136, v135
	v_mul_f32_e32 v135, 0x3fb8aa3b, v137
	v_exp_f32_e32 v137, v135
	v_add_u32_e32 v135, 0xd880, v120
	v_pk_mul_f32 v[16:17], v[16:17], v[136:137]
	ds_read_b128 v[136:139], v134 offset:18432
	ds_read_b128 v[140:143], v134 offset:18464
	s_waitcnt lgkmcnt(1)
	v_mfma_f32_32x32x16_bf16 v[2:17], v[136:139], v[78:81], v[2:17]
	ds_read_b128 v[136:139], v134 offset:18496
	s_waitcnt lgkmcnt(1)
	v_mfma_f32_32x32x16_bf16 v[2:17], v[140:143], v[74:77], v[2:17]
	s_waitcnt lgkmcnt(0)
	v_mfma_f32_32x32x16_bf16 v[2:17], v[136:139], v[70:73], v[2:17]
	ds_read_b128 v[136:139], v134 offset:18528
	s_waitcnt lgkmcnt(0)
	v_mfma_f32_32x32x16_bf16 v[2:17], v[136:139], v[66:69], v[2:17]
	s_nop 0
	s_waitcnt lgkmcnt(0)
	v_mov_b32_e32 v136, v160
	v_mov_b32_e32 v137, v161
	v_mul_f32_e32 v135, 0x3fb8aa3b, v136
	v_exp_f32_e32 v136, v135
	v_mul_f32_e32 v135, 0x3fb8aa3b, v137
	v_exp_f32_e32 v137, v135
	v_add_u32_e32 v135, 0xd888, v120
	v_pk_mul_f32 v[18:19], v[18:19], v[136:137]
	s_nop 0
	s_waitcnt lgkmcnt(0)
	v_mov_b32_e32 v136, v162
	v_mov_b32_e32 v137, v163
	v_mul_f32_e32 v135, 0x3fb8aa3b, v136
	v_exp_f32_e32 v136, v135
	v_mul_f32_e32 v135, 0x3fb8aa3b, v137
	v_exp_f32_e32 v137, v135
	v_add_u32_e32 v135, 0xd8a0, v120
	v_pk_mul_f32 v[20:21], v[20:21], v[136:137]
	s_nop 0
	s_waitcnt lgkmcnt(0)
	v_mov_b32_e32 v136, v164
	v_mov_b32_e32 v137, v165
	v_mul_f32_e32 v135, 0x3fb8aa3b, v136
	v_exp_f32_e32 v136, v135
	v_mul_f32_e32 v135, 0x3fb8aa3b, v137
	v_exp_f32_e32 v137, v135
	v_add_u32_e32 v135, 0xd8a8, v120
	v_pk_mul_f32 v[22:23], v[22:23], v[136:137]
	s_nop 0
	s_waitcnt lgkmcnt(0)
	v_mov_b32_e32 v136, v166
	v_mov_b32_e32 v137, v167
	v_mul_f32_e32 v135, 0x3fb8aa3b, v136
	v_exp_f32_e32 v136, v135
	v_mul_f32_e32 v135, 0x3fb8aa3b, v137
	v_exp_f32_e32 v137, v135
	v_add_u32_e32 v135, 0xd8c0, v120
	v_pk_mul_f32 v[24:25], v[24:25], v[136:137]
	s_nop 0
	s_waitcnt lgkmcnt(0)
	v_mov_b32_e32 v136, v168
	v_mov_b32_e32 v137, v169
	v_mul_f32_e32 v135, 0x3fb8aa3b, v136
	v_exp_f32_e32 v136, v135
	v_mul_f32_e32 v135, 0x3fb8aa3b, v137
	v_exp_f32_e32 v137, v135
	v_add_u32_e32 v135, 0xd8c8, v120
	v_pk_mul_f32 v[26:27], v[26:27], v[136:137]
	s_nop 0
	s_waitcnt lgkmcnt(0)
	v_mov_b32_e32 v136, v170
	v_mov_b32_e32 v137, v171
	v_mul_f32_e32 v135, 0x3fb8aa3b, v136
	v_exp_f32_e32 v136, v135
	v_mul_f32_e32 v135, 0x3fb8aa3b, v137
	v_exp_f32_e32 v137, v135
	v_add_u32_e32 v135, 0xd8e0, v120
	v_pk_mul_f32 v[28:29], v[28:29], v[136:137]
	s_nop 0
	s_waitcnt lgkmcnt(0)
	v_mov_b32_e32 v136, v172
	v_mov_b32_e32 v137, v173
	v_mul_f32_e32 v135, 0x3fb8aa3b, v136
	v_exp_f32_e32 v136, v135
	v_mul_f32_e32 v135, 0x3fb8aa3b, v137
	v_exp_f32_e32 v137, v135
	v_add_u32_e32 v135, 0xd8e8, v120
	v_pk_mul_f32 v[30:31], v[30:31], v[136:137]
	s_nop 0
	s_waitcnt lgkmcnt(0)
	v_mov_b32_e32 v136, v174
	v_mov_b32_e32 v137, v175
	v_mul_f32_e32 v135, 0x3fb8aa3b, v136
	v_exp_f32_e32 v136, v135
	v_mul_f32_e32 v135, 0x3fb8aa3b, v137
	v_exp_f32_e32 v137, v135
	s_nop 0
	v_pk_mul_f32 v[32:33], v[32:33], v[136:137]
	ds_read_b128 v[136:139], v134 offset:23040
	s_waitcnt lgkmcnt(0)
	v_mfma_f32_32x32x16_bf16 v[18:33], v[136:139], v[78:81], v[18:33]
	ds_read_b128 v[78:81], v134 offset:23072
	s_waitcnt lgkmcnt(0)
	v_mfma_f32_32x32x16_bf16 v[18:33], v[78:81], v[74:77], v[18:33]
	ds_read_b128 v[74:77], v134 offset:23104
	s_waitcnt lgkmcnt(0)
	v_mfma_f32_32x32x16_bf16 v[18:33], v[74:77], v[70:73], v[18:33]
	ds_read_b128 v[70:73], v134 offset:23136
	s_waitcnt lgkmcnt(0)
	v_mfma_f32_32x32x16_bf16 v[18:33], v[70:73], v[66:69], v[18:33]
	v_lshl_add_u32 v66, s64, 6, v119
	v_ashrrev_i32_e32 v67, 31, v66
	v_lshlrev_b64 v[66:67], 10, v[66:67]
	v_lshl_add_u64 v[66:67], v[108:109], 0, v[66:67]
	global_store_short v[66:67], v34, off
	v_cvt_pk_bf16_f32 v34, v35, s0
	global_store_short v[66:67], v34, off offset:1024
	v_cvt_pk_bf16_f32 v34, v36, s0
	global_store_short v[66:67], v34, off offset:2048
	v_cvt_pk_bf16_f32 v34, v37, s0
	global_store_short v[66:67], v34, off offset:3072
	v_add_co_u32_e32 v34, vcc, s82, v66
	v_cvt_pk_bf16_f32 v36, v38, s0
	s_nop 0
	v_addc_co_u32_e32 v35, vcc, 0, v67, vcc
	global_store_short v[34:35], v36, off
	v_cvt_pk_bf16_f32 v36, v39, s0
	global_store_short v[34:35], v36, off offset:1024
	v_cvt_pk_bf16_f32 v36, v40, s0
	global_store_short v[34:35], v36, off offset:2048
	v_cvt_pk_bf16_f32 v36, v41, s0
	global_store_short v[34:35], v36, off offset:3072
	v_add_co_u32_e32 v34, vcc, s81, v66
	v_cvt_pk_bf16_f32 v36, v42, s0
	s_nop 0
	v_addc_co_u32_e32 v35, vcc, 0, v67, vcc
	global_store_short v[34:35], v36, off
	v_cvt_pk_bf16_f32 v36, v43, s0
	global_store_short v[34:35], v36, off offset:1024
	v_cvt_pk_bf16_f32 v36, v44, s0
	global_store_short v[34:35], v36, off offset:2048
	v_cvt_pk_bf16_f32 v36, v45, s0
	global_store_short v[34:35], v36, off offset:3072
	v_add_co_u32_e32 v34, vcc, s89, v66
	v_cvt_pk_bf16_f32 v36, v46, s0
	s_nop 0
	v_addc_co_u32_e32 v35, vcc, 0, v67, vcc
	global_store_short v[34:35], v36, off
	v_cvt_pk_bf16_f32 v36, v47, s0
	global_store_short v[34:35], v36, off offset:1024
	v_cvt_pk_bf16_f32 v36, v48, s0
	global_store_short v[34:35], v36, off offset:2048
	v_cvt_pk_bf16_f32 v36, v49, s0
	global_store_short v[34:35], v36, off offset:3072
	s_waitcnt vmcnt(20)
	v_mov_b64_e32 v[38:39], v[62:63]
	s_waitcnt vmcnt(19)
	v_mov_b64_e32 v[34:35], v[58:59]
	v_mov_b64_e32 v[40:41], v[64:65]
	v_mov_b64_e32 v[36:37], v[60:61]
	s_cbranch_scc0 .LBB0_176
